# G0 adaLN partial GEMV inner loop hand-written: 32 weight loads in flight per wave via scalar base + lane offset, same k-ascending fma order
# speedup vs baseline: 1.0083x; 1.0083x over previous
; __global__ void __launch_bounds__(NTHR) fwd_megakernel(Params p) {
;     ...
;   for (int i = gtid; i < 8 * 2 * 12288; i += gthreads) {
;     const int col = i % 12288, l = (i / 12288) & 1, kc = i / (2 * 12288);
;     const float* w = p.w_ada + (size_t)l * 2048 * 12288 + (size_t)(kc * 256) * 12288 + col;
;     float a0 = 0, a1 = 0;
; #pragma unroll 8
;     for (int k = 0; k < 256; ++k) { const float wv = __builtin_nontemporal_load(&w[(size_t)k * 12288]); a0 += csl[kc * 256 + k] * wv; a1 += csl[2048 + kc * 256 + k] * wv; }
;     modp[((size_t)(kc * 2 + l) * 2 + 0) * 12288 + col] = a0; modp[((size_t)(kc * 2 + l) * 2 + 1) * 12288 + col] = a1;
;   }
.LBB0_38:
	v_mul_hi_i32 v2, v1, s9
	v_ashrrev_i32_e32 v4, 11, v2
	v_lshrrev_b32_e32 v5, 31, v2
	v_add_u32_e32 v6, v4, v5
	v_and_b32_e32 v10, 1, v6
	v_ashrrev_i32_e32 v2, 12, v2
	v_mul_i32_i24_e32 v4, 0x3000, v6
	v_add_u32_e32 v11, v2, v5
	v_mul_lo_u32 v2, v10, s10
	v_sub_u32_e32 v4, v1, v4
	v_lshl_add_u64 v[6:7], s[64:65], 0, v[2:3]
	v_lshlrev_b32_e32 v2, 8, v11
	v_mad_i64_i32 v[6:7], s[6:7], v2, s11, v[6:7]
	v_ashrrev_i32_e32 v5, 31, v4
	v_lshl_add_u64 v[8:9], v[4:5], 2, v[6:7]
	v_lshl_add_u32 v2, v11, 10, 0
	s_mov_b64 s[6:7], 0
	v_mov_b32_e32 v6, 0
	v_mov_b32_e32 v7, v3
	v_readfirstlane_b32 s18, v8
	v_readfirstlane_b32 s19, v9
	v_and_b32_e32 v142, 63, v248
	v_lshlrev_b32_e32 v142, 2, v142
	s_mov_b32 s20, 0
	s_nop 4
.Lgemv_k:
	global_load_dword v46, v142, s[18:19] nt
	s_add_u32 s18, s18, 0xc000
	s_addc_u32 s19, s19, 0
	global_load_dword v47, v142, s[18:19] nt
	s_add_u32 s18, s18, 0xc000
	s_addc_u32 s19, s19, 0
	global_load_dword v48, v142, s[18:19] nt
	s_add_u32 s18, s18, 0xc000
	s_addc_u32 s19, s19, 0
	global_load_dword v49, v142, s[18:19] nt
	s_add_u32 s18, s18, 0xc000
	s_addc_u32 s19, s19, 0
	global_load_dword v50, v142, s[18:19] nt
	s_add_u32 s18, s18, 0xc000
	s_addc_u32 s19, s19, 0
	global_load_dword v51, v142, s[18:19] nt
	s_add_u32 s18, s18, 0xc000
	s_addc_u32 s19, s19, 0
	global_load_dword v52, v142, s[18:19] nt
	s_add_u32 s18, s18, 0xc000
	s_addc_u32 s19, s19, 0
	global_load_dword v53, v142, s[18:19] nt
	s_add_u32 s18, s18, 0xc000
	s_addc_u32 s19, s19, 0
	global_load_dword v54, v142, s[18:19] nt
	s_add_u32 s18, s18, 0xc000
	s_addc_u32 s19, s19, 0
	global_load_dword v55, v142, s[18:19] nt
	s_add_u32 s18, s18, 0xc000
	s_addc_u32 s19, s19, 0
	global_load_dword v56, v142, s[18:19] nt
	s_add_u32 s18, s18, 0xc000
	s_addc_u32 s19, s19, 0
	global_load_dword v57, v142, s[18:19] nt
	s_add_u32 s18, s18, 0xc000
	s_addc_u32 s19, s19, 0
	global_load_dword v58, v142, s[18:19] nt
	s_add_u32 s18, s18, 0xc000
	s_addc_u32 s19, s19, 0
	global_load_dword v59, v142, s[18:19] nt
	s_add_u32 s18, s18, 0xc000
	s_addc_u32 s19, s19, 0
	global_load_dword v60, v142, s[18:19] nt
	s_add_u32 s18, s18, 0xc000
	s_addc_u32 s19, s19, 0
	global_load_dword v61, v142, s[18:19] nt
	s_add_u32 s18, s18, 0xc000
	s_addc_u32 s19, s19, 0
	global_load_dword v62, v142, s[18:19] nt
	s_add_u32 s18, s18, 0xc000
	s_addc_u32 s19, s19, 0
	global_load_dword v63, v142, s[18:19] nt
	s_add_u32 s18, s18, 0xc000
	s_addc_u32 s19, s19, 0
	global_load_dword v64, v142, s[18:19] nt
	s_add_u32 s18, s18, 0xc000
	s_addc_u32 s19, s19, 0
	global_load_dword v65, v142, s[18:19] nt
	s_add_u32 s18, s18, 0xc000
	s_addc_u32 s19, s19, 0
	global_load_dword v66, v142, s[18:19] nt
	s_add_u32 s18, s18, 0xc000
	s_addc_u32 s19, s19, 0
	global_load_dword v67, v142, s[18:19] nt
	s_add_u32 s18, s18, 0xc000
	s_addc_u32 s19, s19, 0
	global_load_dword v68, v142, s[18:19] nt
	s_add_u32 s18, s18, 0xc000
	s_addc_u32 s19, s19, 0
	global_load_dword v69, v142, s[18:19] nt
	s_add_u32 s18, s18, 0xc000
	s_addc_u32 s19, s19, 0
	global_load_dword v70, v142, s[18:19] nt
	s_add_u32 s18, s18, 0xc000
	s_addc_u32 s19, s19, 0
	global_load_dword v71, v142, s[18:19] nt
	s_add_u32 s18, s18, 0xc000
	s_addc_u32 s19, s19, 0
	global_load_dword v72, v142, s[18:19] nt
	s_add_u32 s18, s18, 0xc000
	s_addc_u32 s19, s19, 0
	global_load_dword v73, v142, s[18:19] nt
	s_add_u32 s18, s18, 0xc000
	s_addc_u32 s19, s19, 0
	global_load_dword v74, v142, s[18:19] nt
	s_add_u32 s18, s18, 0xc000
	s_addc_u32 s19, s19, 0
	global_load_dword v75, v142, s[18:19] nt
	s_add_u32 s18, s18, 0xc000
	s_addc_u32 s19, s19, 0
	global_load_dword v76, v142, s[18:19] nt
	s_add_u32 s18, s18, 0xc000
	s_addc_u32 s19, s19, 0
	global_load_dword v77, v142, s[18:19] nt
	s_add_u32 s18, s18, 0xc000
	s_addc_u32 s19, s19, 0
	ds_read_b128 v[78:81], v2
	ds_read_b128 v[82:85], v2 offset:16
	ds_read_b128 v[86:89], v2 offset:32
	ds_read_b128 v[90:93], v2 offset:48
	ds_read_b128 v[94:97], v2 offset:64
	ds_read_b128 v[98:101], v2 offset:80
	ds_read_b128 v[102:105], v2 offset:96
	ds_read_b128 v[106:109], v2 offset:112
	ds_read_b128 v[110:113], v2 offset:8192
	ds_read_b128 v[114:117], v2 offset:8208
	ds_read_b128 v[118:121], v2 offset:8224
	ds_read_b128 v[122:125], v2 offset:8240
	ds_read_b128 v[126:129], v2 offset:8256
	ds_read_b128 v[130:133], v2 offset:8272
	ds_read_b128 v[134:137], v2 offset:8288
	ds_read_b128 v[138:141], v2 offset:8304
	v_add_u32_e32 v2, 0x80, v2
	s_waitcnt lgkmcnt(0)
	s_waitcnt vmcnt(24)
	v_fmac_f32_e32 v6, v46, v78
	v_fmac_f32_e32 v7, v46, v110
	v_fmac_f32_e32 v6, v47, v79
	v_fmac_f32_e32 v7, v47, v111
	v_fmac_f32_e32 v6, v48, v80
	v_fmac_f32_e32 v7, v48, v112
	v_fmac_f32_e32 v6, v49, v81
	v_fmac_f32_e32 v7, v49, v113
	v_fmac_f32_e32 v6, v50, v82
	v_fmac_f32_e32 v7, v50, v114
	v_fmac_f32_e32 v6, v51, v83
	v_fmac_f32_e32 v7, v51, v115
	v_fmac_f32_e32 v6, v52, v84
	v_fmac_f32_e32 v7, v52, v116
	v_fmac_f32_e32 v6, v53, v85
	v_fmac_f32_e32 v7, v53, v117
	s_waitcnt vmcnt(16)
	v_fmac_f32_e32 v6, v54, v86
	v_fmac_f32_e32 v7, v54, v118
	v_fmac_f32_e32 v6, v55, v87
	v_fmac_f32_e32 v7, v55, v119
	v_fmac_f32_e32 v6, v56, v88
	v_fmac_f32_e32 v7, v56, v120
	v_fmac_f32_e32 v6, v57, v89
	v_fmac_f32_e32 v7, v57, v121
	v_fmac_f32_e32 v6, v58, v90
	v_fmac_f32_e32 v7, v58, v122
	v_fmac_f32_e32 v6, v59, v91
	v_fmac_f32_e32 v7, v59, v123
	v_fmac_f32_e32 v6, v60, v92
	v_fmac_f32_e32 v7, v60, v124
	v_fmac_f32_e32 v6, v61, v93
	v_fmac_f32_e32 v7, v61, v125
	s_waitcnt vmcnt(8)
	v_fmac_f32_e32 v6, v62, v94
	v_fmac_f32_e32 v7, v62, v126
	v_fmac_f32_e32 v6, v63, v95
	v_fmac_f32_e32 v7, v63, v127
	v_fmac_f32_e32 v6, v64, v96
	v_fmac_f32_e32 v7, v64, v128
	v_fmac_f32_e32 v6, v65, v97
	v_fmac_f32_e32 v7, v65, v129
	v_fmac_f32_e32 v6, v66, v98
	v_fmac_f32_e32 v7, v66, v130
	v_fmac_f32_e32 v6, v67, v99
	v_fmac_f32_e32 v7, v67, v131
	v_fmac_f32_e32 v6, v68, v100
	v_fmac_f32_e32 v7, v68, v132
	v_fmac_f32_e32 v6, v69, v101
	v_fmac_f32_e32 v7, v69, v133
	s_waitcnt vmcnt(0)
	v_fmac_f32_e32 v6, v70, v102
	v_fmac_f32_e32 v7, v70, v134
	v_fmac_f32_e32 v6, v71, v103
	v_fmac_f32_e32 v7, v71, v135
	v_fmac_f32_e32 v6, v72, v104
	v_fmac_f32_e32 v7, v72, v136
	v_fmac_f32_e32 v6, v73, v105
	v_fmac_f32_e32 v7, v73, v137
	v_fmac_f32_e32 v6, v74, v106
	v_fmac_f32_e32 v7, v74, v138
	v_fmac_f32_e32 v6, v75, v107
	v_fmac_f32_e32 v7, v75, v139
	v_fmac_f32_e32 v6, v76, v108
	v_fmac_f32_e32 v7, v76, v140
	v_fmac_f32_e32 v6, v77, v109
	v_fmac_f32_e32 v7, v77, v141
	s_add_u32 s20, s20, 1
	s_cmp_lg_u32 s20, 8
	s_cbranch_scc1 .Lgemv_k
	v_lshl_or_b32 v2, v11, 1, v10
	v_mul_hi_i32_i24_e32 v9, 0x18000, v2
	v_mul_i32_i24_e32 v8, 0x18000, v2
	v_lshl_add_u64 v[8:9], s[4:5], 0, v[8:9]
	v_lshl_add_u64 v[4:5], v[4:5], 2, v[8:9]
	global_store_dword v[4:5], v6, off
	v_add_co_u32_e32 v4, vcc, 0xc000, v4
	v_add_u32_e32 v1, s47, v1
	s_nop 0
	v_addc_co_u32_e32 v5, vcc, 0, v5, vcc
	v_cmp_lt_i32_e32 vcc, s17, v1
	s_or_b64 s[2:3], vcc, s[2:3]
	global_store_dword v[4:5], v7, off
	s_andn2_b64 exec, exec, s[2:3]
	s_cbranch_execnz .LBB0_38
